# grid barrier: L1 invalidate issued at arrival (overlaps the wait) instead of after the release is observed
# speedup vs baseline: 1.0289x; 1.0132x over previous
.LBB0_67:
	s_mov_b64 s[6:7], exec
	s_lshl_b32 s4, s96, 8
	v_mbcnt_lo_u32_b32 v1, s6, 0
	s_add_u32 s4, s86, s4
	v_mbcnt_hi_u32_b32 v1, s7, v1
	s_addc_u32 s5, s87, 0
	v_cmp_eq_u32_e32 vcc, 0, v1
	s_and_saveexec_b64 s[10:11], vcc
	s_cbranch_execz .LBB0_69
	s_bcnt1_i32_b64 s6, s[6:7]
	v_mov_b32_e32 v3, 0x1000
	v_mov_b32_e32 v4, s6
	buffer_inv sc1
	global_atomic_add v3, v3, v4, s[4:5] offset:1024 sc0

.LBB0_82:
	s_or_b64 exec, exec, s[10:11]
	s_waitcnt vmcnt(0)
	s_waitcnt vmcnt(0)

.LBB0_100:
	s_or_b64 exec, exec, s[6:7]
	s_mov_b64 s[6:7], exec
	v_mbcnt_lo_u32_b32 v0, s6, 0
	v_mbcnt_hi_u32_b32 v0, s7, v0
	v_cmp_eq_u32_e32 vcc, 0, v0
	s_waitcnt vmcnt(0)
	s_and_saveexec_b64 s[10:11], vcc
	s_cbranch_execz .LBB0_102
	s_bcnt1_i32_b64 s6, s[6:7]
	v_mov_b32_e32 v0, 0x2000
	v_mov_b32_e32 v1, s6
	global_atomic_add v0, v1, s[4:5] offset:1024

.LBB0_409:
	s_mov_b64 s[4:5], exec
	s_lshl_b32 s2, s96, 8
	v_mbcnt_lo_u32_b32 v1, s4, 0
	s_add_u32 s2, s86, s2
	v_mbcnt_hi_u32_b32 v1, s5, v1
	s_addc_u32 s3, s87, 0
	v_cmp_eq_u32_e32 vcc, 0, v1
	s_and_saveexec_b64 s[6:7], vcc
	s_cbranch_execz .LBB0_411
	s_bcnt1_i32_b64 s4, s[4:5]
	v_mov_b32_e32 v3, 0x1000
	v_mov_b32_e32 v4, s4
	buffer_inv sc1
	global_atomic_add v3, v3, v4, s[2:3] offset:1024 sc0

.LBB0_424:
	s_or_b64 exec, exec, s[6:7]
	s_waitcnt vmcnt(0)
	s_waitcnt vmcnt(0)

.LBB0_442:
	s_or_b64 exec, exec, s[4:5]
	s_mov_b64 s[4:5], exec
	v_mbcnt_lo_u32_b32 v0, s4, 0
	v_mbcnt_hi_u32_b32 v0, s5, v0
	v_cmp_eq_u32_e32 vcc, 0, v0
	s_waitcnt vmcnt(0)
	s_and_saveexec_b64 s[6:7], vcc
	s_cbranch_execz .LBB0_444
	s_bcnt1_i32_b64 s4, s[4:5]
	v_mov_b32_e32 v0, 0x2000
	v_mov_b32_e32 v1, s4
	global_atomic_add v0, v1, s[2:3] offset:1024
